# v39 + sample task: the 8 waves' partial o_c tiles go to per-wave LDS buffers (plain ds_write) and wave 1 sums them in wave order while wave 0 runs the top-k, instead of 32 ds_add_f32 LDS atomics per l
# speedup vs baseline: 1.0199x; 1.0199x over previous
; __device__ __forceinline__ float ex2(float x) { return __builtin_amdgcn_exp2f(x); }
; __device__ __forceinline__ float quad_sum(float v) { v += __int_as_float(dpp_x1(__float_as_int(v))); v += __int_as_float(dpp_x2(__float_as_int(v))); return v; }
; __device__ __forceinline__ void sample_task(const Prm& P, Ctx& C, int task) {
;     ...
;         __syncthreads();
;         float M = NEGB;
; #pragma unroll
;         for (int w = 0; w < 8; ++w) M = fmaxf(M, ml[(w * 32 + q) * 2]);
;         float L = 0.f;
; #pragma unroll
;         for (int w = 0; w < 8; ++w) L += ml[(w * 32 + q) * 2 + 1] * ex2(ml[(w * 32 + q) * 2] - M);
;         const float invl = L > 0.f ? 1.f / L : 0.f;
;         f32x16 o[2]; o[0] = f32x16{}; o[1] = f32x16{};
; #pragma unroll
;         for (int tt = 0; tt < 4; ++tt) { const int tile = C.wave + 8 * tt;
; #pragma unroll
;             for (int r = 0; r < 16; ++r) S[tt][r] = (S[tt][r] > -1e29f) ? ex2(S[tt][r] - M) * invl : 0.f;
; #pragma unroll
;             for (int i = 0; i < 4; ++i) { const float v = quad_sum(S[tt][4 * i] + S[tt][4 * i + 1] + S[tt][4 * i + 2]); if (g == 0) sc[slot * 256 + 8 * tile + 2 * i + hi] = v; }
.LBB0_1494:
	s_or_b64 exec, exec, vcc
	v_add_u32_e32 v0, 0x4000, v197
	s_waitcnt lgkmcnt(0)
	s_barrier
	ds_read2_b64 v[66:69], v0 offset1:32
	ds_read2_b64 v[70:73], v0 offset0:64 offset1:96
	ds_read2_b64 v[74:77], v0 offset0:128 offset1:160
	ds_read2_b64 v[78:81], v0 offset0:192 offset1:224
	s_mov_b32 s78, 0xf149f2ca
	s_waitcnt lgkmcnt(3)
	v_max3_f32 v0, v66, s78, v68
	s_waitcnt lgkmcnt(2)
	v_max3_f32 v0, v0, v70, v72
	s_waitcnt lgkmcnt(1)
	v_max3_f32 v0, v0, v74, v76
	s_waitcnt lgkmcnt(0)
	v_max3_f32 v0, v0, v78, v80
	v_sub_f32_e32 v66, v66, v0
	v_exp_f32_e32 v171, v66
	v_sub_f32_e32 v66, v68, v0
	v_exp_f32_e32 v170, v66
	v_sub_f32_e32 v68, v70, v0
	v_mov_b32_e32 v66, v69
	v_exp_f32_e32 v69, v68
	v_sub_f32_e32 v68, v72, v0
	v_exp_f32_e32 v68, v68
	v_pk_mul_f32 v[66:67], v[66:67], v[170:171]
	v_mov_b32_e32 v70, v73
	v_add_f32_e32 v67, 0, v67
	v_add_f32_e32 v72, v66, v67
	v_pk_mul_f32 v[66:67], v[68:69], v[70:71]
	v_sub_f32_e32 v68, v74, v0
	v_exp_f32_e32 v69, v68
	v_sub_f32_e32 v68, v76, v0
	v_exp_f32_e32 v68, v68
	v_add_f32_e32 v67, v67, v72
	v_mov_b32_e32 v74, v77
	v_add_f32_e32 v70, v66, v67
	v_pk_mul_f32 v[66:67], v[68:69], v[74:75]
	v_sub_f32_e32 v68, v78, v0
	v_exp_f32_e32 v69, v68
	v_sub_f32_e32 v68, v80, v0
	v_exp_f32_e32 v68, v68
	v_add_f32_e32 v67, v67, v70
	v_mov_b32_e32 v78, v81
	v_add_f32_e32 v70, v66, v67
	v_pk_mul_f32 v[66:67], v[68:69], v[78:79]
	v_sub_f32_e32 v50, v50, v0
	v_add_f32_e32 v67, v67, v70
	v_add_f32_e32 v66, v66, v67
	v_div_scale_f32 v67, s[82:83], v66, v66, 1.0
	v_rcp_f32_e32 v68, v67
	v_exp_f32_e32 v50, v50
	v_sub_f32_e32 v53, v53, v0
	v_exp_f32_e32 v53, v53
	v_fma_f32 v69, -v67, v68, 1.0
	v_fmac_f32_e32 v68, v69, v68
	v_div_scale_f32 v69, vcc, 1.0, v66, 1.0
	v_mul_f32_e32 v70, v69, v68
	v_fma_f32 v71, -v67, v70, v69
	v_fmac_f32_e32 v70, v71, v68
	v_fma_f32 v67, -v67, v70, v69
	v_div_fmas_f32 v67, v67, v68, v70
	v_div_fixup_f32 v67, v67, v66, 1.0
	v_cmp_lt_f32_e32 vcc, 0, v66
	v_sub_f32_e32 v66, v51, v0
	v_sub_f32_e32 v51, v52, v0
	v_exp_f32_e32 v51, v51
	v_exp_f32_e32 v52, v66
	v_cndmask_b32_e32 v170, 0, v67, vcc
	v_pk_mul_f32 v[50:51], v[50:51], v[170:171] op_sel_hi:[1,0]
	s_nop 0
	v_cndmask_b32_e64 v66, 0, v51, s[76:77]
	v_cndmask_b32_e64 v67, 0, v50, s[74:75]
	v_pk_mul_f32 v[50:51], v[52:53], v[170:171] op_sel_hi:[1,0]
	s_nop 0
	v_cndmask_b32_e64 v50, 0, v50, s[72:73]
	v_add_f32_e32 v52, v67, v50
	v_add_f32_e32 v52, v66, v52
	s_nop 1
	v_add_f32_dpp v52, v52, v52 quad_perm:[1,0,3,2] row_mask:0xf bank_mask:0xf bound_ctrl:1
	s_nop 1
	v_mov_b32_dpp v53, v52 quad_perm:[2,3,0,1] row_mask:0xf bank_mask:0xf bound_ctrl:1
	s_mov_b64 s[72:73], exec
	v_readlane_b32 s74, v251, 0
	v_readlane_b32 s75, v251, 1
	s_and_b64 s[74:75], s[72:73], s[74:75]
	s_mov_b64 exec, s[74:75]
	v_add_f32_e32 v52, v52, v53
	ds_write_b32 v179, v52
	s_or_b64 exec, exec, s[72:73]
	v_sub_f32_e32 v53, v55, v0
	v_sub_f32_e32 v52, v54, v0
	v_exp_f32_e32 v54, v53
	v_sub_f32_e32 v53, v56, v0
	v_sub_f32_e32 v55, v57, v0
	v_exp_f32_e32 v52, v52
	v_exp_f32_e32 v53, v53
	v_exp_f32_e32 v55, v55
	v_mov_b32_e32 v171, v170
	v_pk_mul_f32 v[56:57], v[52:53], v[170:171]
	v_pk_mul_f32 v[52:53], v[54:55], v[170:171]
	v_cndmask_b32_e64 v68, 0, v56, s[64:65]
	v_cndmask_b32_e64 v69, 0, v52, s[66:67]
	v_cndmask_b32_e64 v57, 0, v57, s[70:71]
	v_add_f32_e32 v52, v68, v69
	v_add_f32_e32 v52, v57, v52
	s_nop 1
	v_add_f32_dpp v52, v52, v52 quad_perm:[1,0,3,2] row_mask:0xf bank_mask:0xf bound_ctrl:1
	s_nop 1
	v_mov_b32_dpp v54, v52 quad_perm:[2,3,0,1] row_mask:0xf bank_mask:0xf bound_ctrl:1
	s_mov_b64 s[64:65], exec
	v_readlane_b32 s66, v251, 0
	v_readlane_b32 s67, v251, 1
	s_and_b64 s[66:67], s[64:65], s[66:67]
	s_mov_b64 exec, s[66:67]
	v_add_f32_e32 v52, v52, v54
	ds_write_b32 v179, v52 offset:8
	s_or_b64 exec, exec, s[64:65]
	v_sub_f32_e32 v52, v58, v0
	v_exp_f32_e32 v54, v52
	v_sub_f32_e32 v52, v59, v0
	v_exp_f32_e32 v58, v52
	v_sub_f32_e32 v52, v60, v0
	v_exp_f32_e32 v55, v52
	v_sub_f32_e32 v52, v61, v0
	v_exp_f32_e32 v59, v52
	v_pk_mul_f32 v[60:61], v[54:55], v[170:171]
	s_nop 0
	v_cndmask_b32_e64 v52, 0, v60, s[60:61]
	v_pk_mul_f32 v[54:55], v[58:59], v[170:171]
	v_cndmask_b32_e64 v56, 0, v61, s[68:69]
	v_cndmask_b32_e64 v54, 0, v54, s[62:63]
	v_add_f32_e32 v58, v52, v54
	v_add_f32_e32 v58, v56, v58
	s_nop 1
	v_add_f32_dpp v58, v58, v58 quad_perm:[1,0,3,2] row_mask:0xf bank_mask:0xf bound_ctrl:1
	s_nop 1
	v_mov_b32_dpp v59, v58 quad_perm:[2,3,0,1] row_mask:0xf bank_mask:0xf bound_ctrl:1
	s_mov_b64 s[60:61], exec
	v_readlane_b32 s62, v251, 0
	v_readlane_b32 s63, v251, 1
	s_and_b64 s[62:63], s[60:61], s[62:63]
	s_mov_b64 exec, s[62:63]
	v_add_f32_e32 v58, v58, v59
	ds_write_b32 v179, v58 offset:16
	s_or_b64 exec, exec, s[60:61]
	v_cndmask_b32_e64 v58, 0, v53, s[48:49]
	v_sub_f32_e32 v53, v62, v0
	v_exp_f32_e32 v60, v53
	v_sub_f32_e32 v53, v63, v0
	v_exp_f32_e32 v62, v53
	v_sub_f32_e32 v53, v64, v0
	v_exp_f32_e32 v61, v53
	v_sub_f32_e32 v53, v65, v0
	v_exp_f32_e32 v63, v53
	v_cndmask_b32_e64 v59, 0, v51, s[46:47]
	v_pk_mul_f32 v[60:61], v[60:61], v[170:171]
	v_cndmask_b32_e64 v51, 0, v55, s[58:59]
	v_pk_mul_f32 v[62:63], v[62:63], v[170:171]
	v_cndmask_b32_e64 v53, 0, v61, s[54:55]
	v_cndmask_b32_e64 v55, 0, v60, s[50:51]
	v_cndmask_b32_e64 v61, 0, v62, s[52:53]
	v_add_f32_e32 v62, v55, v61
	v_add_f32_e32 v62, v53, v62
	v_cndmask_b32_e64 v60, 0, v63, s[56:57]
	s_nop 0
	v_add_f32_dpp v62, v62, v62 quad_perm:[1,0,3,2] row_mask:0xf bank_mask:0xf bound_ctrl:1
	s_nop 1
	v_mov_b32_dpp v63, v62 quad_perm:[2,3,0,1] row_mask:0xf bank_mask:0xf bound_ctrl:1
	s_mov_b64 s[46:47], exec
	v_readlane_b32 s48, v251, 0
	v_readlane_b32 s49, v251, 1
	s_and_b64 s[48:49], s[46:47], s[48:49]
	s_mov_b64 exec, s[48:49]
	v_add_f32_e32 v62, v62, v63
	ds_write_b32 v179, v62 offset:24
	s_or_b64 exec, exec, s[46:47]
	v_bfe_u32 v63, v69, 16, 1
	s_movk_i32 s46, 0x7fff
	v_add3_u32 v63, v69, v63, s46
	v_bfe_u32 v62, v67, 16, 1
	v_bfe_u32 v65, v50, 16, 1
	v_add3_u32 v62, v67, v62, s46
	s_waitcnt vmcnt(15)
; #define LAS __attribute__((address_space(3)))
; __device__ __forceinline__ float ex2(float x) { return __builtin_amdgcn_exp2f(x); }
; #define LDS_WAIT() asm volatile("s_waitcnt lgkmcnt(0)" ::: "memory")
; #define MFMA32(a, b, c) __builtin_amdgcn_mfma_f32_32x32x16_bf16((a), (b), (c), 0, 0, 0)
; __device__ __forceinline__ float quad_sum(float v) { v += __int_as_float(dpp_x1(__float_as_int(v))); v += __int_as_float(dpp_x2(__float_as_int(v))); return v; }
; __device__ __forceinline__ void sample_task(const Prm& P, Ctx& C, int task) {
;     ...
;         for (int tt = 0; tt < 4; ++tt) { const int tile = C.wave + 8 * tt;
; #pragma unroll
;             for (int r = 0; r < 16; ++r) S[tt][r] = (S[tt][r] > -1e29f) ? ex2(S[tt][r] - M) * invl : 0.f;
; #pragma unroll
;             for (int i = 0; i < 4; ++i) { const float v = quad_sum(S[tt][4 * i] + S[tt][4 * i + 1] + S[tt][4 * i + 2]); if (g == 0) sc[slot * 256 + 8 * tile + 2 * i + hi] = v; }
;             {
;                 const int key = lane >> 1, d0 = 32 * (lane & 1);
; #pragma unroll
;                 for (int c = 0; c < 4; ++c) { const unsigned w[4] = {vld[tt][c].x, vld[tt][c].y, vld[tt][c].z, vld[tt][c].w};
; #pragma unroll
;                     for (int e = 0; e < 4; ++e) { vts[(d0 + 8 * c + 2 * e) * 36 + key] = (bf16_t)(w[e] & 0xffffu); vts[(d0 + 8 * c + 2 * e + 1) * 36 + key] = (bf16_t)(w[e] >> 16); } }
;             }
;             LDS_WAIT();
;             bf16x8 pf[2]; pf[0] = pack8(S[tt], 0); pf[1] = pack8(S[tt], 8);
; #pragma unroll
;             for (int dblk = 0; dblk < 2; ++dblk)
; #pragma unroll
;                 for (int ks = 0; ks < 2; ++ks) { const LAS bf16_t* vp = vts + (32 * dblk + q) * 36 + 16 * ks + 4 * hi;
;                     const s16x4 lo = *(const LAS s16x4*)vp, hh = *(const LAS s16x4*)(vp + 8);
;                     o[dblk] = MFMA32(((bf16x8){lo[0], lo[1], lo[2], lo[3], hh[0], hh[1], hh[2], hh[3]}), pf[ks], o[dblk]); }
;             LDS_WAIT();
	ds_write_b16 v181, v142 offset:18432
	ds_write_b16_d16_hi v181, v142 offset:18504
	ds_write_b16 v181, v143 offset:18576
	ds_write_b16_d16_hi v181, v143 offset:18648
	ds_write_b16 v181, v144 offset:18720
	ds_write_b16_d16_hi v181, v144 offset:18792
	ds_write_b16 v181, v145 offset:18864
	ds_write_b16_d16_hi v181, v145 offset:18936
	s_waitcnt vmcnt(14)
	ds_write_b16 v181, v138 offset:19008
	ds_write_b16_d16_hi v181, v138 offset:19080
	ds_write_b16 v181, v139 offset:19152
	ds_write_b16_d16_hi v181, v139 offset:19224
	ds_write_b16 v181, v140 offset:19296
	ds_write_b16_d16_hi v181, v140 offset:19368
	ds_write_b16 v181, v141 offset:19440
	ds_write_b16_d16_hi v181, v141 offset:19512
	s_waitcnt vmcnt(13)
	ds_write_b16 v181, v134 offset:19584
	ds_write_b16_d16_hi v181, v134 offset:19656
	ds_write_b16 v181, v135 offset:19728
	ds_write_b16_d16_hi v181, v135 offset:19800
	ds_write_b16 v181, v136 offset:19872
	ds_write_b16_d16_hi v181, v136 offset:19944
	ds_write_b16 v181, v137 offset:20016
	ds_write_b16_d16_hi v181, v137 offset:20088
	s_waitcnt vmcnt(12)
	ds_write_b16 v181, v130 offset:20160
	ds_write_b16_d16_hi v181, v130 offset:20232
	ds_write_b16 v181, v131 offset:20304
	ds_write_b16_d16_hi v181, v131 offset:20376
	ds_write_b16 v181, v132 offset:20448
	ds_write_b16_d16_hi v181, v132 offset:20520
	ds_write_b16 v181, v133 offset:20592
	ds_write_b16_d16_hi v181, v133 offset:20664
	v_add3_u32 v50, v50, v65, s46
	v_lshrrev_b32_e32 v62, 16, v62
	s_mov_b32 s47, 0xffff0000
	s_waitcnt lgkmcnt(0)
	v_cvt_pk_bf16_f32 v69, v57, v58
	v_cvt_pk_bf16_f32 v67, v66, v59
	v_and_or_b32 v66, v50, s47, v62
	v_bfe_u32 v50, v60, 16, 1
	v_bfe_u32 v57, v61, 16, 1
	v_bfe_u32 v58, v51, 16, 1
	v_bfe_u32 v59, v54, 16, 1
	v_add_u32_e32 v130, 0x4800, v201
	v_add3_u32 v74, v54, v59, s46
	v_add3_u32 v75, v51, v58, s46
	v_add3_u32 v76, v61, v57, s46
	v_add3_u32 v77, v60, v50, s46
	ds_read2_b64 v[58:61], v130 offset1:2
	v_bfe_u32 v65, v68, 16, 1
	v_add3_u32 v65, v68, v65, s46
	v_lshrrev_b32_e32 v65, 16, v65
	v_bfe_u32 v50, v52, 16, 1
	v_and_or_b32 v68, v63, s47, v65
	v_bfe_u32 v51, v56, 16, 1
	v_bfe_u32 v54, v55, 16, 1
	v_bfe_u32 v57, v53, 16, 1
	v_add3_u32 v50, v52, v50, s46
	ds_read2_b64 v[70:73], v130 offset0:4 offset1:6
	v_add3_u32 v78, v53, v57, s46
	v_add3_u32 v79, v55, v54, s46
	v_add3_u32 v80, v56, v51, s46
	v_lshrrev_b32_e32 v81, 16, v50
	s_waitcnt lgkmcnt(1)
	v_mfma_f32_32x32x16_bf16 v[50:65], v[58:61], v[66:69], 0
	v_lshrrev_b32_e32 v80, 16, v80
	v_lshrrev_b32_e32 v79, 16, v79
	v_lshrrev_b32_e32 v78, 16, v78
	v_and_or_b32 v135, v77, s47, v78
	v_and_or_b32 v134, v76, s47, v79
	v_and_or_b32 v133, v75, s47, v80
	v_and_or_b32 v132, v74, s47, v81
	v_add_u32_e32 v131, 0x5000, v201
	ds_read2_b64 v[136:139], v131 offset0:36 offset1:38
	s_waitcnt lgkmcnt(1)
	v_mfma_f32_32x32x16_bf16 v[50:65], v[70:73], v[132:135], v[50:65]
	ds_read2_b64 v[70:73], v131 offset0:32 offset1:34
	v_sub_f32_e32 v2, v2, v0
	v_exp_f32_e32 v2, v2
	v_sub_f32_e32 v5, v5, v0
	v_exp_f32_e32 v5, v5
	s_waitcnt lgkmcnt(0)
	s_waitcnt lgkmcnt(0)
	v_mfma_f32_32x32x16_bf16 v[66:81], v[70:73], v[66:69], 0
	v_mfma_f32_32x32x16_bf16 v[66:81], v[136:139], v[132:135], v[66:81]
	v_sub_f32_e32 v132, v3, v0
	v_sub_f32_e32 v3, v4, v0
	v_exp_f32_e32 v3, v3
	v_exp_f32_e32 v4, v132
	v_pk_mul_f32 v[2:3], v[2:3], v[170:171]
	s_nop 0
	v_cndmask_b32_e64 v132, 0, v3, s[40:41]
	v_cndmask_b32_e64 v133, 0, v2, s[38:39]
	v_pk_mul_f32 v[2:3], v[4:5], v[170:171]
	s_nop 0
	v_cndmask_b32_e64 v2, 0, v2, s[44:45]
	v_add_f32_e32 v4, v133, v2
	v_add_f32_e32 v4, v132, v4
	s_nop 1
	v_add_f32_dpp v4, v4, v4 quad_perm:[1,0,3,2] row_mask:0xf bank_mask:0xf bound_ctrl:1
	s_nop 1
	v_mov_b32_dpp v5, v4 quad_perm:[2,3,0,1] row_mask:0xf bank_mask:0xf bound_ctrl:1
	s_mov_b64 s[38:39], exec
	v_readlane_b32 s40, v251, 0
	v_readlane_b32 s41, v251, 1
	s_and_b64 s[40:41], s[38:39], s[40:41]
	s_mov_b64 exec, s[40:41]
	v_add_f32_e32 v4, v4, v5
	ds_write_b32 v179, v4 offset:256
	s_or_b64 exec, exec, s[38:39]
	v_sub_f32_e32 v5, v7, v0
	v_sub_f32_e32 v4, v6, v0
	v_exp_f32_e32 v6, v5
	v_sub_f32_e32 v5, v8, v0
	v_sub_f32_e32 v7, v9, v0
	v_exp_f32_e32 v4, v4
	v_exp_f32_e32 v5, v5
	v_exp_f32_e32 v7, v7
	v_pk_mul_f32 v[8:9], v[4:5], v[170:171]
	v_pk_mul_f32 v[4:5], v[6:7], v[170:171]
	v_cndmask_b32_e64 v135, 0, v8, s[30:31]
	v_cndmask_b32_e64 v136, 0, v4, s[34:35]
	v_cndmask_b32_e64 v134, 0, v9, s[42:43]
	v_add_f32_e32 v4, v135, v136
	v_add_f32_e32 v4, v134, v4
	s_nop 1
	v_add_f32_dpp v4, v4, v4 quad_perm:[1,0,3,2] row_mask:0xf bank_mask:0xf bound_ctrl:1
	s_nop 1
	v_mov_b32_dpp v6, v4 quad_perm:[2,3,0,1] row_mask:0xf bank_mask:0xf bound_ctrl:1
	s_mov_b64 s[30:31], exec
	v_readlane_b32 s34, v251, 0
	v_readlane_b32 s35, v251, 1
	s_and_b64 s[34:35], s[30:31], s[34:35]
	s_mov_b64 exec, s[34:35]
	v_add_f32_e32 v4, v4, v6
	ds_write_b32 v179, v4 offset:264
	s_or_b64 exec, exec, s[30:31]
	v_sub_f32_e32 v4, v10, v0
	v_exp_f32_e32 v6, v4
	v_sub_f32_e32 v4, v11, v0
	v_exp_f32_e32 v8, v4
	v_sub_f32_e32 v4, v12, v0
	v_exp_f32_e32 v7, v4
	v_sub_f32_e32 v4, v13, v0
	v_exp_f32_e32 v9, v4
	v_pk_mul_f32 v[12:13], v[6:7], v[170:171]
	s_nop 0
	v_cndmask_b32_e64 v4, 0, v12, s[24:25]
	v_pk_mul_f32 v[6:7], v[8:9], v[170:171]
	v_cndmask_b32_e64 v10, 0, v13, s[36:37]
	v_cndmask_b32_e64 v6, 0, v6, s[26:27]
	v_add_f32_e32 v8, v4, v6
	v_add_f32_e32 v8, v10, v8
	s_nop 1
	v_add_f32_dpp v8, v8, v8 quad_perm:[1,0,3,2] row_mask:0xf bank_mask:0xf bound_ctrl:1
	s_nop 1
	v_mov_b32_dpp v9, v8 quad_perm:[2,3,0,1] row_mask:0xf bank_mask:0xf bound_ctrl:1
	s_mov_b64 s[24:25], exec
	v_readlane_b32 s26, v251, 0
	v_readlane_b32 s27, v251, 1
	s_and_b64 s[26:27], s[24:25], s[26:27]
	s_mov_b64 exec, s[26:27]
	v_add_f32_e32 v8, v8, v9
	ds_write_b32 v179, v8 offset:272
	s_or_b64 exec, exec, s[24:25]
	v_sub_f32_e32 v9, v15, v0
	v_sub_f32_e32 v8, v14, v0
	v_exp_f32_e32 v12, v9
	v_sub_f32_e32 v9, v16, v0
	v_sub_f32_e32 v11, v17, v0
	v_exp_f32_e32 v8, v8
	v_exp_f32_e32 v9, v9
	v_exp_f32_e32 v13, v11
	v_pk_mul_f32 v[14:15], v[8:9], v[170:171]
	v_pk_mul_f32 v[8:9], v[12:13], v[170:171]
	v_cndmask_b32_e64 v12, 0, v14, s[20:21]
	v_cndmask_b32_e64 v8, 0, v8, s[22:23]
	v_cndmask_b32_e64 v11, 0, v15, s[28:29]
	v_add_f32_e32 v13, v12, v8
	v_add_f32_e32 v13, v11, v13
	s_nop 1
	v_add_f32_dpp v13, v13, v13 quad_perm:[1,0,3,2] row_mask:0xf bank_mask:0xf bound_ctrl:1
	s_nop 1
	v_mov_b32_dpp v14, v13 quad_perm:[2,3,0,1] row_mask:0xf bank_mask:0xf bound_ctrl:1
	s_mov_b64 s[20:21], exec
	v_readlane_b32 s22, v251, 0
	v_readlane_b32 s23, v251, 1
	s_and_b64 s[22:23], s[20:21], s[22:23]
	s_mov_b64 exec, s[22:23]
	v_add_f32_e32 v13, v13, v14
	ds_write_b32 v179, v13 offset:280
	s_or_b64 exec, exec, s[20:21]
	v_cndmask_b32_e64 v3, 0, v3, s[8:9]
	v_cndmask_b32_e64 v5, 0, v5, s[10:11]
	s_movk_i32 s8, 0x7fff
	v_cndmask_b32_e64 v7, 0, v7, s[16:17]
	v_cndmask_b32_e64 v9, 0, v9, s[18:19]
	s_waitcnt vmcnt(11)
; #define LAS __attribute__((address_space(3)))
; __device__ __forceinline__ float ex2(float x) { return __builtin_amdgcn_exp2f(x); }
; #define LDS_WAIT() asm volatile("s_waitcnt lgkmcnt(0)" ::: "memory")
; #define MFMA32(a, b, c) __builtin_amdgcn_mfma_f32_32x32x16_bf16((a), (b), (c), 0, 0, 0)
; __device__ __forceinline__ float quad_sum(float v) { v += __int_as_float(dpp_x1(__float_as_int(v))); v += __int_as_float(dpp_x2(__float_as_int(v))); return v; }
; __device__ __forceinline__ void sample_task(const Prm& P, Ctx& C, int task) {
;     ...
;         for (int tt = 0; tt < 4; ++tt) { const int tile = C.wave + 8 * tt;
; #pragma unroll
;             for (int r = 0; r < 16; ++r) S[tt][r] = (S[tt][r] > -1e29f) ? ex2(S[tt][r] - M) * invl : 0.f;
; #pragma unroll
;             for (int i = 0; i < 4; ++i) { const float v = quad_sum(S[tt][4 * i] + S[tt][4 * i + 1] + S[tt][4 * i + 2]); if (g == 0) sc[slot * 256 + 8 * tile + 2 * i + hi] = v; }
;             {
;                 const int key = lane >> 1, d0 = 32 * (lane & 1);
; #pragma unroll
;                 for (int c = 0; c < 4; ++c) { const unsigned w[4] = {vld[tt][c].x, vld[tt][c].y, vld[tt][c].z, vld[tt][c].w};
; #pragma unroll
;                     for (int e = 0; e < 4; ++e) { vts[(d0 + 8 * c + 2 * e) * 36 + key] = (bf16_t)(w[e] & 0xffffu); vts[(d0 + 8 * c + 2 * e + 1) * 36 + key] = (bf16_t)(w[e] >> 16); } }
;             }
;             LDS_WAIT();
;             bf16x8 pf[2]; pf[0] = pack8(S[tt], 0); pf[1] = pack8(S[tt], 8);
; #pragma unroll
;             for (int dblk = 0; dblk < 2; ++dblk)
; #pragma unroll
;                 for (int ks = 0; ks < 2; ++ks) { const LAS bf16_t* vp = vts + (32 * dblk + q) * 36 + 16 * ks + 4 * hi;
;                     const s16x4 lo = *(const LAS s16x4*)vp, hh = *(const LAS s16x4*)(vp + 8);
;                     o[dblk] = MFMA32(((bf16x8){lo[0], lo[1], lo[2], lo[3], hh[0], hh[1], hh[2], hh[3]}), pf[ks], o[dblk]); }
;             LDS_WAIT();
	ds_write_b16 v181, v126 offset:18432
	ds_write_b16_d16_hi v181, v126 offset:18504
	ds_write_b16 v181, v127 offset:18576
	ds_write_b16_d16_hi v181, v127 offset:18648
	ds_write_b16 v181, v128 offset:18720
	ds_write_b16_d16_hi v181, v128 offset:18792
	ds_write_b16 v181, v129 offset:18864
	ds_write_b16_d16_hi v181, v129 offset:18936
	s_waitcnt vmcnt(10)
	ds_write_b16 v181, v122 offset:19008
	ds_write_b16_d16_hi v181, v122 offset:19080
	ds_write_b16 v181, v123 offset:19152
	ds_write_b16_d16_hi v181, v123 offset:19224
	ds_write_b16 v181, v124 offset:19296
	ds_write_b16_d16_hi v181, v124 offset:19368
	ds_write_b16 v181, v125 offset:19440
	ds_write_b16_d16_hi v181, v125 offset:19512
	s_waitcnt vmcnt(9)
	ds_write_b16 v181, v118 offset:19584
	ds_write_b16_d16_hi v181, v118 offset:19656
	ds_write_b16 v181, v119 offset:19728
	ds_write_b16_d16_hi v181, v119 offset:19800
	ds_write_b16 v181, v120 offset:19872
	ds_write_b16_d16_hi v181, v120 offset:19944
	ds_write_b16 v181, v121 offset:20016
	ds_write_b16_d16_hi v181, v121 offset:20088
	s_waitcnt vmcnt(8)
	ds_write_b16 v181, v114 offset:20160
	ds_write_b16_d16_hi v181, v114 offset:20232
	ds_write_b16 v181, v115 offset:20304
	ds_write_b16_d16_hi v181, v115 offset:20376
	ds_write_b16 v181, v116 offset:20448
	ds_write_b16_d16_hi v181, v116 offset:20520
	ds_write_b16 v181, v117 offset:20592
	ds_write_b16_d16_hi v181, v117 offset:20664
	s_mov_b32 s9, 0xffff0000
	s_waitcnt lgkmcnt(0)
	v_cvt_pk_bf16_f32 v17, v134, v5
	v_cvt_pk_bf16_f32 v16, v135, v136
	v_cvt_pk_bf16_f32 v15, v132, v3
	v_cvt_pk_bf16_f32 v14, v133, v2
	v_bfe_u32 v2, v9, 16, 1
	v_bfe_u32 v3, v8, 16, 1
	v_bfe_u32 v5, v7, 16, 1
	v_bfe_u32 v13, v6, 16, 1
	v_add3_u32 v13, v6, v13, s8
	v_add3_u32 v114, v7, v5, s8
	v_add3_u32 v115, v8, v3, s8
	v_add3_u32 v116, v9, v2, s8
	ds_read2_b64 v[6:9], v130 offset1:2
	v_bfe_u32 v2, v4, 16, 1
	v_bfe_u32 v3, v10, 16, 1
	v_bfe_u32 v5, v12, 16, 1
	v_bfe_u32 v117, v11, 16, 1
	v_add3_u32 v2, v4, v2, s8
	v_add3_u32 v11, v11, v117, s8
	v_add3_u32 v12, v12, v5, s8
	v_add3_u32 v10, v10, v3, s8
	v_lshrrev_b32_e32 v117, 16, v2
	ds_read2_b64 v[2:5], v130 offset0:4 offset1:6
	s_waitcnt lgkmcnt(1)
	v_mfma_f32_32x32x16_bf16 v[50:65], v[6:9], v[14:17], v[50:65]
	v_lshrrev_b32_e32 v6, 16, v10
	v_lshrrev_b32_e32 v7, 16, v12
	v_lshrrev_b32_e32 v8, 16, v11
	v_and_or_b32 v9, v116, s9, v8
	v_and_or_b32 v8, v115, s9, v7
	v_and_or_b32 v7, v114, s9, v6
	v_and_or_b32 v6, v13, s9, v117
	s_waitcnt lgkmcnt(0)
	s_nop 0
	v_mfma_f32_32x32x16_bf16 v[50:65], v[2:5], v[6:9], v[50:65]
	ds_read2_b64 v[2:5], v131 offset0:32 offset1:34
	s_waitcnt lgkmcnt(0)
	v_mfma_f32_32x32x16_bf16 v[66:81], v[2:5], v[14:17], v[66:81]
	ds_read2_b64 v[2:5], v131 offset0:36 offset1:38
	s_waitcnt lgkmcnt(0)
	s_waitcnt lgkmcnt(0)
	v_mfma_f32_32x32x16_bf16 v[66:81], v[2:5], v[6:9], v[66:81]
	v_sub_f32_e32 v2, v18, v0
	v_sub_f32_e32 v3, v20, v0
	v_exp_f32_e32 v2, v2
	v_sub_f32_e32 v4, v19, v0
	v_exp_f32_e32 v3, v3
	v_sub_f32_e32 v5, v21, v0
	v_exp_f32_e32 v4, v4
	v_exp_f32_e32 v5, v5
	v_pk_mul_f32 v[2:3], v[2:3], v[170:171]
	s_nop 0
	v_cndmask_b32_e64 v10, 0, v3, s[6:7]
	v_cndmask_b32_e64 v11, 0, v2, s[0:1]
	v_pk_mul_f32 v[2:3], v[4:5], v[170:171]
	s_nop 0
	v_cndmask_b32_e64 v2, 0, v2, s[2:3]
	v_add_f32_e32 v4, v11, v2
	v_add_f32_e32 v4, v10, v4
	s_nop 1
	v_add_f32_dpp v4, v4, v4 quad_perm:[1,0,3,2] row_mask:0xf bank_mask:0xf bound_ctrl:1
	s_nop 1
	v_mov_b32_dpp v5, v4 quad_perm:[2,3,0,1] row_mask:0xf bank_mask:0xf bound_ctrl:1
	s_mov_b64 s[0:1], exec
	v_readlane_b32 s2, v251, 0
	v_readlane_b32 s3, v251, 1
	s_and_b64 s[2:3], s[0:1], s[2:3]
	s_mov_b64 exec, s[2:3]
	v_add_f32_e32 v4, v4, v5
	ds_write_b32 v179, v4 offset:512
	s_or_b64 exec, exec, s[0:1]
	v_sub_f32_e32 v5, v23, v0
	v_sub_f32_e32 v4, v22, v0
	v_exp_f32_e32 v6, v5
	v_sub_f32_e32 v5, v24, v0
	v_sub_f32_e32 v7, v25, v0
	v_exp_f32_e32 v4, v4
	v_exp_f32_e32 v5, v5
	v_exp_f32_e32 v7, v7
	v_pk_mul_f32 v[8:9], v[4:5], v[170:171]
	v_pk_mul_f32 v[4:5], v[6:7], v[170:171]
	v_cndmask_b32_e64 v14, 0, v8, s[92:93]
	v_cndmask_b32_e64 v15, 0, v4, s[94:95]
	v_cndmask_b32_e64 v13, 0, v9, s[4:5]
	v_add_f32_e32 v4, v14, v15
	v_add_f32_e32 v4, v13, v4
	s_nop 1
	v_add_f32_dpp v4, v4, v4 quad_perm:[1,0,3,2] row_mask:0xf bank_mask:0xf bound_ctrl:1
	s_nop 1
	v_mov_b32_dpp v6, v4 quad_perm:[2,3,0,1] row_mask:0xf bank_mask:0xf bound_ctrl:1
	s_mov_b64 s[0:1], exec
	v_readlane_b32 s2, v251, 0
	v_readlane_b32 s3, v251, 1
	s_and_b64 s[2:3], s[0:1], s[2:3]
	s_mov_b64 exec, s[2:3]
	v_add_f32_e32 v4, v4, v6
	ds_write_b32 v179, v4 offset:520
	s_or_b64 exec, exec, s[0:1]
	v_sub_f32_e32 v4, v26, v0
	v_exp_f32_e32 v6, v4
	v_sub_f32_e32 v4, v27, v0
	v_exp_f32_e32 v8, v4
	v_sub_f32_e32 v4, v28, v0
	v_exp_f32_e32 v7, v4
	v_sub_f32_e32 v4, v29, v0
	v_exp_f32_e32 v9, v4
	v_pk_mul_f32 v[16:17], v[6:7], v[170:171]
	s_nop 0
	v_cndmask_b32_e64 v4, 0, v16, s[88:89]
	v_pk_mul_f32 v[6:7], v[8:9], v[170:171]
	v_cndmask_b32_e64 v12, 0, v17, s[96:97]
	v_cndmask_b32_e64 v6, 0, v6, s[90:91]
	v_add_f32_e32 v8, v4, v6
	v_add_f32_e32 v8, v12, v8
	s_nop 1
	v_add_f32_dpp v8, v8, v8 quad_perm:[1,0,3,2] row_mask:0xf bank_mask:0xf bound_ctrl:1
	s_nop 1
	v_mov_b32_dpp v9, v8 quad_perm:[2,3,0,1] row_mask:0xf bank_mask:0xf bound_ctrl:1
	s_mov_b64 s[0:1], exec
	v_readlane_b32 s2, v251, 0
	v_readlane_b32 s3, v251, 1
	s_and_b64 s[2:3], s[0:1], s[2:3]
	s_mov_b64 exec, s[2:3]
	v_add_f32_e32 v8, v8, v9
	ds_write_b32 v179, v8 offset:528
	s_or_b64 exec, exec, s[0:1]
	v_sub_f32_e32 v9, v31, v0
	v_sub_f32_e32 v8, v30, v0
	v_exp_f32_e32 v16, v9
	v_sub_f32_e32 v9, v32, v0
	v_sub_f32_e32 v17, v33, v0
	v_exp_f32_e32 v8, v8
	v_exp_f32_e32 v9, v9
	v_exp_f32_e32 v17, v17
	v_pk_mul_f32 v[18:19], v[8:9], v[170:171]
	v_pk_mul_f32 v[8:9], v[16:17], v[170:171]
	v_cndmask_b32_e64 v17, 0, v18, s[84:85]
	v_cndmask_b32_e64 v8, 0, v8, s[86:87]
	v_cndmask_b32_e64 v16, 0, v19, s[14:15]
	v_add_f32_e32 v18, v17, v8
	v_add_f32_e32 v18, v16, v18
	s_nop 1
	v_add_f32_dpp v18, v18, v18 quad_perm:[1,0,3,2] row_mask:0xf bank_mask:0xf bound_ctrl:1
	s_nop 1
	v_mov_b32_dpp v19, v18 quad_perm:[2,3,0,1] row_mask:0xf bank_mask:0xf bound_ctrl:1
	s_mov_b64 s[0:1], exec
	v_readlane_b32 s2, v251, 0
	v_readlane_b32 s3, v251, 1
	s_and_b64 s[2:3], s[0:1], s[2:3]
	s_mov_b64 exec, s[2:3]
	v_add_f32_e32 v18, v18, v19
	ds_write_b32 v179, v18 offset:536
	s_or_b64 exec, exec, s[0:1]
	v_readlane_b32 s0, v253, 30
	v_readlane_b32 s1, v253, 31
	s_nop 1
	v_cndmask_b32_e64 v3, 0, v3, s[0:1]
	v_readlane_b32 s0, v253, 32
	v_readlane_b32 s1, v253, 33
	v_cndmask_b32_e64 v9, 0, v9, s[12:13]
	s_nop 0
	v_cndmask_b32_e64 v5, 0, v5, s[0:1]
	v_readlane_b32 s0, v253, 34
	v_readlane_b32 s1, v253, 35
	s_waitcnt vmcnt(7)
; #define LAS __attribute__((address_space(3)))
; __device__ __forceinline__ float ex2(float x) { return __builtin_amdgcn_exp2f(x); }
; #define LDS_WAIT() asm volatile("s_waitcnt lgkmcnt(0)" ::: "memory")
; #define MFMA32(a, b, c) __builtin_amdgcn_mfma_f32_32x32x16_bf16((a), (b), (c), 0, 0, 0)
; __device__ __forceinline__ float quad_sum(float v) { v += __int_as_float(dpp_x1(__float_as_int(v))); v += __int_as_float(dpp_x2(__float_as_int(v))); return v; }
; __device__ __forceinline__ void sample_task(const Prm& P, Ctx& C, int task) {
;     ...
;         for (int tt = 0; tt < 4; ++tt) { const int tile = C.wave + 8 * tt;
; #pragma unroll
;             for (int r = 0; r < 16; ++r) S[tt][r] = (S[tt][r] > -1e29f) ? ex2(S[tt][r] - M) * invl : 0.f;
; #pragma unroll
;             for (int i = 0; i < 4; ++i) { const float v = quad_sum(S[tt][4 * i] + S[tt][4 * i + 1] + S[tt][4 * i + 2]); if (g == 0) sc[slot * 256 + 8 * tile + 2 * i + hi] = v; }
;             {
;                 const int key = lane >> 1, d0 = 32 * (lane & 1);
; #pragma unroll
;                 for (int c = 0; c < 4; ++c) { const unsigned w[4] = {vld[tt][c].x, vld[tt][c].y, vld[tt][c].z, vld[tt][c].w};
; #pragma unroll
;                     for (int e = 0; e < 4; ++e) { vts[(d0 + 8 * c + 2 * e) * 36 + key] = (bf16_t)(w[e] & 0xffffu); vts[(d0 + 8 * c + 2 * e + 1) * 36 + key] = (bf16_t)(w[e] >> 16); } }
;             }
;             LDS_WAIT();
;             bf16x8 pf[2]; pf[0] = pack8(S[tt], 0); pf[1] = pack8(S[tt], 8);
; #pragma unroll
;             for (int dblk = 0; dblk < 2; ++dblk)
; #pragma unroll
;                 for (int ks = 0; ks < 2; ++ks) { const LAS bf16_t* vp = vts + (32 * dblk + q) * 36 + 16 * ks + 4 * hi;
;                     const s16x4 lo = *(const LAS s16x4*)vp, hh = *(const LAS s16x4*)(vp + 8);
;                     o[dblk] = MFMA32(((bf16x8){lo[0], lo[1], lo[2], lo[3], hh[0], hh[1], hh[2], hh[3]}), pf[ks], o[dblk]); }
;             LDS_WAIT();
	ds_write_b16 v181, v110 offset:18432
	ds_write_b16_d16_hi v181, v110 offset:18504
	ds_write_b16 v181, v111 offset:18576
	ds_write_b16_d16_hi v181, v111 offset:18648
	ds_write_b16 v181, v112 offset:18720
	ds_write_b16_d16_hi v181, v112 offset:18792
	ds_write_b16 v181, v113 offset:18864
	ds_write_b16_d16_hi v181, v113 offset:18936
	s_waitcnt vmcnt(6)
	ds_write_b16 v181, v106 offset:19008
	ds_write_b16_d16_hi v181, v106 offset:19080
	ds_write_b16 v181, v107 offset:19152
	ds_write_b16_d16_hi v181, v107 offset:19224
	ds_write_b16 v181, v108 offset:19296
	ds_write_b16_d16_hi v181, v108 offset:19368
	ds_write_b16 v181, v109 offset:19440
	ds_write_b16_d16_hi v181, v109 offset:19512
	s_waitcnt vmcnt(5)
	ds_write_b16 v181, v102 offset:19584
	ds_write_b16_d16_hi v181, v102 offset:19656
	ds_write_b16 v181, v103 offset:19728
	ds_write_b16_d16_hi v181, v103 offset:19800
	ds_write_b16 v181, v104 offset:19872
	ds_write_b16_d16_hi v181, v104 offset:19944
	ds_write_b16 v181, v105 offset:20016
	ds_write_b16_d16_hi v181, v105 offset:20088
	s_waitcnt vmcnt(4)
	ds_write_b16 v181, v98 offset:20160
	ds_write_b16_d16_hi v181, v98 offset:20232
	ds_write_b16 v181, v99 offset:20304
	ds_write_b16_d16_hi v181, v99 offset:20376
	ds_write_b16 v181, v100 offset:20448
	ds_write_b16_d16_hi v181, v100 offset:20520
	ds_write_b16 v181, v101 offset:20592
	ds_write_b16_d16_hi v181, v101 offset:20664
	v_cndmask_b32_e64 v7, 0, v7, s[0:1]
	s_movk_i32 s0, 0x7fff
	s_mov_b32 s1, 0xffff0000
	s_waitcnt lgkmcnt(0)
	v_cvt_pk_bf16_f32 v21, v13, v5
	v_cvt_pk_bf16_f32 v19, v10, v3
	v_cvt_pk_bf16_f32 v18, v11, v2
	v_bfe_u32 v2, v9, 16, 1
	v_bfe_u32 v3, v8, 16, 1
	v_bfe_u32 v5, v7, 16, 1
	v_bfe_u32 v10, v6, 16, 1
	v_cvt_pk_bf16_f32 v20, v14, v15
	v_add3_u32 v10, v6, v10, s0
	v_add3_u32 v11, v7, v5, s0
	v_add3_u32 v13, v8, v3, s0
	v_add3_u32 v14, v9, v2, s0
	ds_read2_b64 v[6:9], v130 offset1:2
	v_bfe_u32 v2, v4, 16, 1
	v_bfe_u32 v3, v12, 16, 1
	v_bfe_u32 v5, v17, 16, 1
	v_bfe_u32 v15, v16, 16, 1
	v_add3_u32 v2, v4, v2, s0
	v_add3_u32 v15, v16, v15, s0
	v_add3_u32 v16, v17, v5, s0
	v_add3_u32 v12, v12, v3, s0
	v_lshrrev_b32_e32 v17, 16, v2
	ds_read2_b64 v[2:5], v130 offset0:4 offset1:6
	s_waitcnt lgkmcnt(1)
	v_mfma_f32_32x32x16_bf16 v[50:65], v[6:9], v[18:21], v[50:65]
	v_lshrrev_b32_e32 v6, 16, v12
	v_lshrrev_b32_e32 v7, 16, v16
	v_lshrrev_b32_e32 v8, 16, v15
	v_and_or_b32 v9, v14, s1, v8
	v_and_or_b32 v8, v13, s1, v7
	v_and_or_b32 v7, v11, s1, v6
	v_and_or_b32 v6, v10, s1, v17
	v_readlane_b32 s0, v253, 40
	v_readlane_b32 s1, v253, 41
	s_waitcnt lgkmcnt(0)
	v_mfma_f32_32x32x16_bf16 v[50:65], v[2:5], v[6:9], v[50:65]
	ds_read2_b64 v[2:5], v131 offset0:32 offset1:34
	s_waitcnt lgkmcnt(0)
	v_mfma_f32_32x32x16_bf16 v[66:81], v[2:5], v[18:21], v[66:81]
	ds_read2_b64 v[2:5], v131 offset0:36 offset1:38
	s_waitcnt lgkmcnt(0)
	s_waitcnt lgkmcnt(0)
	v_mfma_f32_32x32x16_bf16 v[66:81], v[2:5], v[6:9], v[66:81]
	v_sub_f32_e32 v2, v34, v0
	v_sub_f32_e32 v3, v36, v0
	v_exp_f32_e32 v2, v2
	v_exp_f32_e32 v3, v3
	v_sub_f32_e32 v4, v35, v0
	v_sub_f32_e32 v5, v37, v0
	v_exp_f32_e32 v4, v4
	v_exp_f32_e32 v5, v5
	v_pk_mul_f32 v[2:3], v[2:3], v[170:171]
	s_nop 0
	v_cndmask_b32_e64 v10, 0, v3, s[0:1]
	v_readlane_b32 s0, v253, 36
	v_readlane_b32 s1, v253, 37
	s_nop 1
	v_cndmask_b32_e64 v11, 0, v2, s[0:1]
	v_readlane_b32 s0, v253, 38
	v_pk_mul_f32 v[2:3], v[4:5], v[170:171]
	v_readlane_b32 s1, v253, 39
	s_nop 1
	v_cndmask_b32_e64 v2, 0, v2, s[0:1]
	v_add_f32_e32 v4, v11, v2
	v_add_f32_e32 v4, v10, v4
	s_nop 1
	v_add_f32_dpp v4, v4, v4 quad_perm:[1,0,3,2] row_mask:0xf bank_mask:0xf bound_ctrl:1
	s_nop 1
	v_mov_b32_dpp v5, v4 quad_perm:[2,3,0,1] row_mask:0xf bank_mask:0xf bound_ctrl:1
	s_mov_b64 s[0:1], exec
	v_readlane_b32 s2, v251, 0
	v_readlane_b32 s3, v251, 1
	s_and_b64 s[2:3], s[0:1], s[2:3]
	s_mov_b64 exec, s[2:3]
	v_add_f32_e32 v4, v4, v5
	ds_write_b32 v179, v4 offset:768
	s_or_b64 exec, exec, s[0:1]
	v_sub_f32_e32 v5, v39, v0
	v_sub_f32_e32 v4, v38, v0
	v_exp_f32_e32 v6, v5
	v_sub_f32_e32 v5, v40, v0
	v_exp_f32_e32 v4, v4
	v_exp_f32_e32 v5, v5
	v_sub_f32_e32 v7, v41, v0
	v_readlane_b32 s0, v253, 48
	v_exp_f32_e32 v7, v7
	v_pk_mul_f32 v[8:9], v[4:5], v[170:171]
	v_readlane_b32 s1, v253, 49
	v_pk_mul_f32 v[4:5], v[6:7], v[170:171]
	s_nop 0
	v_cndmask_b32_e64 v13, 0, v9, s[0:1]
	v_readlane_b32 s0, v253, 44
	v_readlane_b32 s1, v253, 45
	s_nop 1
	v_cndmask_b32_e64 v14, 0, v8, s[0:1]
	v_readlane_b32 s0, v253, 46
	v_readlane_b32 s1, v253, 47
	s_nop 1
	v_cndmask_b32_e64 v15, 0, v4, s[0:1]
	v_add_f32_e32 v4, v14, v15
	v_add_f32_e32 v4, v13, v4
	s_nop 1
	v_add_f32_dpp v4, v4, v4 quad_perm:[1,0,3,2] row_mask:0xf bank_mask:0xf bound_ctrl:1
	s_nop 1
	v_mov_b32_dpp v6, v4 quad_perm:[2,3,0,1] row_mask:0xf bank_mask:0xf bound_ctrl:1
	s_mov_b64 s[0:1], exec
	v_readlane_b32 s2, v251, 0
	v_readlane_b32 s3, v251, 1
	s_and_b64 s[2:3], s[0:1], s[2:3]
	s_mov_b64 exec, s[2:3]
	v_add_f32_e32 v4, v4, v6
	ds_write_b32 v179, v4 offset:776
	s_or_b64 exec, exec, s[0:1]
	v_sub_f32_e32 v4, v42, v0
	v_exp_f32_e32 v6, v4
	v_sub_f32_e32 v4, v43, v0
	v_exp_f32_e32 v8, v4
	v_sub_f32_e32 v4, v44, v0
	v_exp_f32_e32 v7, v4
	v_sub_f32_e32 v4, v45, v0
	v_readlane_b32 s0, v253, 56
	v_exp_f32_e32 v9, v4
	v_pk_mul_f32 v[16:17], v[6:7], v[170:171]
	v_readlane_b32 s1, v253, 57
	v_pk_mul_f32 v[6:7], v[8:9], v[170:171]
	s_nop 0
	v_cndmask_b32_e64 v4, 0, v17, s[0:1]
	v_readlane_b32 s0, v253, 52
	v_readlane_b32 s1, v253, 53
	s_nop 1
	v_cndmask_b32_e64 v12, 0, v16, s[0:1]
	v_readlane_b32 s0, v253, 54
	v_readlane_b32 s1, v253, 55
	s_nop 1
	v_cndmask_b32_e64 v6, 0, v6, s[0:1]
	v_add_f32_e32 v8, v12, v6
	v_add_f32_e32 v8, v4, v8
	s_nop 1
; #define LAS __attribute__((address_space(3)))
; #define LDS_WAIT() asm volatile("s_waitcnt lgkmcnt(0)" ::: "memory")
; #define MFMA32(a, b, c) __builtin_amdgcn_mfma_f32_32x32x16_bf16((a), (b), (c), 0, 0, 0)
; __device__ __forceinline__ void sample_task(const Prm& P, Ctx& C, int task) {
;     ...
;             bf16x8 pf[2]; pf[0] = pack8(S[tt], 0); pf[1] = pack8(S[tt], 8);
; #pragma unroll
;             for (int dblk = 0; dblk < 2; ++dblk)
; #pragma unroll
;                 for (int ks = 0; ks < 2; ++ks) { const LAS bf16_t* vp = vts + (32 * dblk + q) * 36 + 16 * ks + 4 * hi;
;                     const s16x4 lo = *(const LAS s16x4*)vp, hh = *(const LAS s16x4*)(vp + 8);
;                     o[dblk] = MFMA32(((bf16x8){lo[0], lo[1], lo[2], lo[3], hh[0], hh[1], hh[2], hh[3]}), pf[ks], o[dblk]); }
;             LDS_WAIT();
;         }
; #pragma unroll
;         for (int dblk = 0; dblk < 2; ++dblk)
; #pragma unroll
;             for (int r = 0; r < 16; ++r) atomicAdd((float*)(oacc + (dblk * 16 + r) * 64 + lane), o[dblk][r]);
	v_add_f32_dpp v8, v8, v8 quad_perm:[1,0,3,2] row_mask:0xf bank_mask:0xf bound_ctrl:1
	s_nop 1
	v_mov_b32_dpp v9, v8 quad_perm:[2,3,0,1] row_mask:0xf bank_mask:0xf bound_ctrl:1
	s_mov_b64 s[0:1], exec
	v_readlane_b32 s2, v251, 0
	v_readlane_b32 s3, v251, 1
	s_and_b64 s[2:3], s[0:1], s[2:3]
	s_mov_b64 exec, s[2:3]
	v_add_f32_e32 v8, v8, v9
	ds_write_b32 v179, v8 offset:784
	s_or_b64 exec, exec, s[0:1]
	v_sub_f32_e32 v9, v47, v0
	v_sub_f32_e32 v8, v46, v0
	v_exp_f32_e32 v16, v9
	v_sub_f32_e32 v9, v48, v0
	v_exp_f32_e32 v8, v8
	v_exp_f32_e32 v9, v9
	v_sub_f32_e32 v0, v49, v0
	v_exp_f32_e32 v17, v0
	v_readlane_b32 s0, v252, 0
	v_pk_mul_f32 v[18:19], v[8:9], v[170:171]
	v_readlane_b32 s1, v252, 1
	v_pk_mul_f32 v[8:9], v[16:17], v[170:171]
	s_nop 0
	v_cndmask_b32_e64 v0, 0, v19, s[0:1]
	v_readlane_b32 s0, v253, 60
	v_readlane_b32 s1, v253, 61
	s_nop 1
	v_cndmask_b32_e64 v16, 0, v18, s[0:1]
	v_readlane_b32 s0, v253, 62
	v_readlane_b32 s1, v253, 63
	s_nop 1
	v_cndmask_b32_e64 v8, 0, v8, s[0:1]
	v_add_f32_e32 v17, v16, v8
	v_add_f32_e32 v17, v0, v17
	s_nop 1
	v_add_f32_dpp v17, v17, v17 quad_perm:[1,0,3,2] row_mask:0xf bank_mask:0xf bound_ctrl:1
	s_nop 1
	v_mov_b32_dpp v18, v17 quad_perm:[2,3,0,1] row_mask:0xf bank_mask:0xf bound_ctrl:1
	s_mov_b64 s[0:1], exec
	v_readlane_b32 s2, v251, 0
	v_readlane_b32 s3, v251, 1
	s_and_b64 s[2:3], s[0:1], s[2:3]
	s_mov_b64 exec, s[2:3]
	v_add_f32_e32 v17, v17, v18
	ds_write_b32 v179, v17 offset:792
	s_or_b64 exec, exec, s[0:1]
	v_readlane_b32 s0, v253, 42
	v_readlane_b32 s1, v253, 43
	s_nop 1
	v_cndmask_b32_e64 v3, 0, v3, s[0:1]
	v_readlane_b32 s0, v253, 50
	v_readlane_b32 s1, v253, 51
	s_waitcnt vmcnt(3)
	ds_write_b16 v181, v94 offset:18432
	ds_write_b16_d16_hi v181, v94 offset:18504
	ds_write_b16 v181, v95 offset:18576
	ds_write_b16_d16_hi v181, v95 offset:18648
	ds_write_b16 v181, v96 offset:18720
	ds_write_b16_d16_hi v181, v96 offset:18792
	ds_write_b16 v181, v97 offset:18864
	ds_write_b16_d16_hi v181, v97 offset:18936
	s_waitcnt vmcnt(2)
	ds_write_b16 v181, v90 offset:19008
	ds_write_b16_d16_hi v181, v90 offset:19080
	ds_write_b16 v181, v91 offset:19152
	ds_write_b16_d16_hi v181, v91 offset:19224
	ds_write_b16 v181, v92 offset:19296
	ds_write_b16_d16_hi v181, v92 offset:19368
	ds_write_b16 v181, v93 offset:19440
	ds_write_b16_d16_hi v181, v93 offset:19512
	s_waitcnt vmcnt(1)
	ds_write_b16 v181, v86 offset:19584
	ds_write_b16_d16_hi v181, v86 offset:19656
	ds_write_b16 v181, v87 offset:19728
	ds_write_b16_d16_hi v181, v87 offset:19800
	ds_write_b16 v181, v88 offset:19872
	ds_write_b16_d16_hi v181, v88 offset:19944
	ds_write_b16 v181, v89 offset:20016
	ds_write_b16_d16_hi v181, v89 offset:20088
	s_waitcnt vmcnt(0)
	ds_write_b16 v181, v82 offset:20160
	ds_write_b16_d16_hi v181, v82 offset:20232
	ds_write_b16 v181, v83 offset:20304
	ds_write_b16_d16_hi v181, v83 offset:20376
	ds_write_b16 v181, v84 offset:20448
	ds_write_b16_d16_hi v181, v84 offset:20520
	ds_write_b16 v181, v85 offset:20592
	ds_write_b16_d16_hi v181, v85 offset:20664
	v_cndmask_b32_e64 v5, 0, v5, s[0:1]
	v_readlane_b32 s0, v253, 58
	v_readlane_b32 s1, v253, 59
	s_waitcnt lgkmcnt(0)
	s_movk_i32 s24, 0x7fff
	v_cndmask_b32_e64 v7, 0, v7, s[0:1]
	v_readlane_b32 s0, v252, 2
	v_readlane_b32 s1, v252, 3
	s_nop 1
	v_cndmask_b32_e64 v9, 0, v9, s[0:1]
	s_movk_i32 s0, 0x7fff
	s_mov_b32 s1, 0xffff0000
	v_cvt_pk_bf16_f32 v21, v13, v5
	v_cvt_pk_bf16_f32 v19, v10, v3
	v_cvt_pk_bf16_f32 v18, v11, v2
	v_bfe_u32 v2, v9, 16, 1
	v_bfe_u32 v3, v8, 16, 1
	v_bfe_u32 v5, v7, 16, 1
	v_bfe_u32 v10, v6, 16, 1
	v_cvt_pk_bf16_f32 v20, v14, v15
	v_add3_u32 v10, v6, v10, s0
	v_add3_u32 v11, v7, v5, s0
	v_add3_u32 v13, v8, v3, s0
	v_add3_u32 v14, v9, v2, s0
	ds_read2_b64 v[6:9], v130 offset1:2
	v_bfe_u32 v2, v12, 16, 1
	v_bfe_u32 v3, v4, 16, 1
	v_bfe_u32 v5, v16, 16, 1
	v_bfe_u32 v15, v0, 16, 1
	v_add3_u32 v2, v12, v2, s0
	v_add3_u32 v0, v0, v15, s0
	v_add3_u32 v15, v16, v5, s0
	v_add3_u32 v16, v4, v3, s0
	v_lshrrev_b32_e32 v12, 16, v2
	ds_read2_b64 v[2:5], v130 offset0:4 offset1:6
	s_waitcnt lgkmcnt(1)
	v_mfma_f32_32x32x16_bf16 v[50:65], v[6:9], v[18:21], v[50:65]
	v_lshrrev_b32_e32 v6, 16, v16
	v_lshrrev_b32_e32 v7, 16, v15
	v_lshrrev_b32_e32 v0, 16, v0
	v_and_or_b32 v9, v14, s1, v0
	v_and_or_b32 v8, v13, s1, v7
	v_and_or_b32 v7, v11, s1, v6
	v_and_or_b32 v6, v10, s1, v12
	v_readlane_b32 s0, v250, 62
	v_readlane_b32 s1, v250, 63
	s_waitcnt lgkmcnt(0)
	v_mfma_f32_32x32x16_bf16 v[50:65], v[2:5], v[6:9], v[50:65]
	ds_read2_b64 v[2:5], v131 offset0:32 offset1:34
	s_andn2_b64 vcc, exec, s[0:1]
	s_waitcnt lgkmcnt(0)
	v_mfma_f32_32x32x16_bf16 v[66:81], v[2:5], v[18:21], v[66:81]
	ds_read2_b64 v[2:5], v131 offset0:36 offset1:38
	s_waitcnt lgkmcnt(0)
	s_waitcnt lgkmcnt(0)
	v_mfma_f32_32x32x16_bf16 v[66:81], v[2:5], v[6:9], v[66:81]
	s_nop 4
	v_readlane_b32 s0, v251, 55
	s_lshl_b32 s0, s0, 7
	s_add_i32 s0, s0, 0x12000
	v_add_u32_e32 v0, s0, v183
	ds_write_b32 v0, v50 offset:8192
	ds_write_b32 v0, v51 offset:8448
	ds_write_b32 v0, v52 offset:8704
	ds_write_b32 v0, v53 offset:8960
	ds_write_b32 v0, v54 offset:9216
	ds_write_b32 v0, v55 offset:9472
	ds_write_b32 v0, v56 offset:9728
	ds_write_b32 v0, v57 offset:9984
	ds_write_b32 v0, v58 offset:10240
	ds_write_b32 v0, v59 offset:10496
	ds_write_b32 v0, v60 offset:10752
	ds_write_b32 v0, v61 offset:11008
	ds_write_b32 v0, v62 offset:11264
	ds_write_b32 v0, v63 offset:11520
	ds_write_b32 v0, v64 offset:11776
	ds_write_b32 v0, v65 offset:12032
	ds_write_b32 v0, v66 offset:12288
	ds_write_b32 v0, v67 offset:12544
	ds_write_b32 v0, v68 offset:12800
	ds_write_b32 v0, v69 offset:13056
	ds_write_b32 v0, v70 offset:13312
	ds_write_b32 v0, v71 offset:13568
	ds_write_b32 v0, v72 offset:13824
	ds_write_b32 v0, v73 offset:14080
	ds_write_b32 v0, v74 offset:14336
	ds_write_b32 v0, v75 offset:14592
	ds_write_b32 v0, v76 offset:14848
	ds_write_b32 v0, v77 offset:15104
	ds_write_b32 v0, v78 offset:15360
	ds_write_b32 v0, v79 offset:15616
	ds_write_b32 v0, v80 offset:15872
	ds_write_b32 v0, v81 offset:16128
	s_waitcnt lgkmcnt(0)
	s_barrier
	s_cbranch_vccnz .Locs_w
	s_branch .Lw0_topk
; __device__ __forceinline__ int crow(int r, int hi) { return (r & 3) + 8 * (r >> 2) + 4 * hi; }
; __device__ __forceinline__ void sample_task(const Prm& P, Ctx& C, int task) {
;     ...
;         if (C.wave == 0) {
;             if (slot == ts) { const float gate = ((const float*)(P.ws + WS_G))[row * 24 + head * 3 + 0];
; #pragma unroll
;                 for (int dblk = 0; dblk < 2; ++dblk)
; #pragma unroll
;                     for (int r = 0; r < 16; ++r) ocs[g * 64 + 32 * dblk + crow(r, hi)] = oacc[(dblk * 16 + r) * 64 + lane] * gate; }
.Locs_w:
	v_readlane_b32 s0, v251, 55
	s_cmp_lg_u32 s0, 64
	s_cbranch_scc1 .LBB0_1555
	v_readlane_b32 s0, v251, 2
	s_nop 1
	v_cmp_eq_u32_e32 vcc, s0, v173
	s_and_saveexec_b64 s[0:1], vcc
	s_cbranch_execz .Locs_done
	s_mul_i32 s2, s81, 0x60
	s_mul_hi_u32 s3, s80, 0x60
	s_add_i32 s3, s3, s2
	s_mul_i32 s2, s80, 0x60
	v_readlane_b32 s4, v251, 21
	v_mul_u32_u24_e32 v0, 3, v172
	s_add_u32 s2, s4, s2
	v_readlane_b32 s4, v251, 22
	s_addc_u32 s3, s4, s3
	v_lshlrev_b32_e32 v0, 2, v0
	global_load_dword v0, v0, s[2:3]
	v_add_u32_e32 v20, 0x12000, v183
	v_add_u32_e32 v21, 0x1a000, v183
	ds_read_b32 v4, v20 offset:8192
	ds_read_b32 v5, v20 offset:8448
	ds_read_b32 v6, v20 offset:8704
	ds_read_b32 v7, v20 offset:8960
	ds_read_b32 v8, v20 offset:9216
	ds_read_b32 v9, v20 offset:9472
	ds_read_b32 v10, v20 offset:9728
	ds_read_b32 v11, v20 offset:9984
	ds_read_b32 v12, v20 offset:16384
	ds_read_b32 v13, v20 offset:16640
	ds_read_b32 v14, v20 offset:16896
	ds_read_b32 v15, v20 offset:17152
	ds_read_b32 v16, v20 offset:17408
	ds_read_b32 v17, v20 offset:17664
	ds_read_b32 v18, v20 offset:17920
	ds_read_b32 v19, v20 offset:18176
	s_waitcnt lgkmcnt(0)
	v_add_f32_e32 v4, v4, v12
	v_add_f32_e32 v5, v5, v13
	v_add_f32_e32 v6, v6, v14
	v_add_f32_e32 v7, v7, v15
	v_add_f32_e32 v8, v8, v16
	v_add_f32_e32 v9, v9, v17
	v_add_f32_e32 v10, v10, v18
	v_add_f32_e32 v11, v11, v19
	ds_read_b32 v12, v20 offset:24576
	ds_read_b32 v13, v20 offset:24832
	ds_read_b32 v14, v20 offset:25088
	ds_read_b32 v15, v20 offset:25344
	ds_read_b32 v16, v20 offset:25600
	ds_read_b32 v17, v20 offset:25856
	ds_read_b32 v18, v20 offset:26112
	ds_read_b32 v19, v20 offset:26368
	s_waitcnt lgkmcnt(0)
	v_add_f32_e32 v4, v4, v12
	v_add_f32_e32 v5, v5, v13
	v_add_f32_e32 v6, v6, v14
	v_add_f32_e32 v7, v7, v15
	v_add_f32_e32 v8, v8, v16
	v_add_f32_e32 v9, v9, v17
	v_add_f32_e32 v10, v10, v18
	v_add_f32_e32 v11, v11, v19
	ds_read_b32 v12, v20 offset:32768
	ds_read_b32 v13, v20 offset:33024
	ds_read_b32 v14, v20 offset:33280
	ds_read_b32 v15, v20 offset:33536
	ds_read_b32 v16, v20 offset:33792
	ds_read_b32 v17, v20 offset:34048
	ds_read_b32 v18, v20 offset:34304
	ds_read_b32 v19, v20 offset:34560
	s_waitcnt lgkmcnt(0)
	v_add_f32_e32 v4, v4, v12
	v_add_f32_e32 v5, v5, v13
	v_add_f32_e32 v6, v6, v14
	v_add_f32_e32 v7, v7, v15
	v_add_f32_e32 v8, v8, v16
	v_add_f32_e32 v9, v9, v17
	v_add_f32_e32 v10, v10, v18
	v_add_f32_e32 v11, v11, v19
	ds_read_b32 v12, v21 offset:8192
	ds_read_b32 v13, v21 offset:8448
	ds_read_b32 v14, v21 offset:8704
	ds_read_b32 v15, v21 offset:8960
	ds_read_b32 v16, v21 offset:9216
	ds_read_b32 v17, v21 offset:9472
	ds_read_b32 v18, v21 offset:9728
	ds_read_b32 v19, v21 offset:9984
	s_waitcnt lgkmcnt(0)
	v_add_f32_e32 v4, v4, v12
	v_add_f32_e32 v5, v5, v13
	v_add_f32_e32 v6, v6, v14
	v_add_f32_e32 v7, v7, v15
	v_add_f32_e32 v8, v8, v16
	v_add_f32_e32 v9, v9, v17
	v_add_f32_e32 v10, v10, v18
	v_add_f32_e32 v11, v11, v19
	ds_read_b32 v12, v21 offset:16384
	ds_read_b32 v13, v21 offset:16640
	ds_read_b32 v14, v21 offset:16896
	ds_read_b32 v15, v21 offset:17152
	ds_read_b32 v16, v21 offset:17408
	ds_read_b32 v17, v21 offset:17664
	ds_read_b32 v18, v21 offset:17920
	ds_read_b32 v19, v21 offset:18176
	s_waitcnt lgkmcnt(0)
	v_add_f32_e32 v4, v4, v12
	v_add_f32_e32 v5, v5, v13
	v_add_f32_e32 v6, v6, v14
	v_add_f32_e32 v7, v7, v15
	v_add_f32_e32 v8, v8, v16
	v_add_f32_e32 v9, v9, v17
	v_add_f32_e32 v10, v10, v18
	v_add_f32_e32 v11, v11, v19
	ds_read_b32 v12, v21 offset:24576
	ds_read_b32 v13, v21 offset:24832
	ds_read_b32 v14, v21 offset:25088
	ds_read_b32 v15, v21 offset:25344
	ds_read_b32 v16, v21 offset:25600
	ds_read_b32 v17, v21 offset:25856
	ds_read_b32 v18, v21 offset:26112
	ds_read_b32 v19, v21 offset:26368
	s_waitcnt lgkmcnt(0)
	v_add_f32_e32 v4, v4, v12
	v_add_f32_e32 v5, v5, v13
	v_add_f32_e32 v6, v6, v14
	v_add_f32_e32 v7, v7, v15
	v_add_f32_e32 v8, v8, v16
	v_add_f32_e32 v9, v9, v17
	v_add_f32_e32 v10, v10, v18
	v_add_f32_e32 v11, v11, v19
	ds_read_b32 v12, v21 offset:32768
	ds_read_b32 v13, v21 offset:33024
	ds_read_b32 v14, v21 offset:33280
	ds_read_b32 v15, v21 offset:33536
	ds_read_b32 v16, v21 offset:33792
	ds_read_b32 v17, v21 offset:34048
	ds_read_b32 v18, v21 offset:34304
	ds_read_b32 v19, v21 offset:34560
	s_waitcnt lgkmcnt(0)
	v_add_f32_e32 v4, v4, v12
	v_add_f32_e32 v5, v5, v13
	v_add_f32_e32 v6, v6, v14
	v_add_f32_e32 v7, v7, v15
	v_add_f32_e32 v8, v8, v16
	v_add_f32_e32 v9, v9, v17
	v_add_f32_e32 v10, v10, v18
	v_add_f32_e32 v11, v11, v19
	s_waitcnt vmcnt(0)
	v_mul_f32_e32 v4, v0, v4
	v_mul_f32_e32 v5, v0, v5
	v_mul_f32_e32 v6, v0, v6
	v_mul_f32_e32 v7, v0, v7
	v_mul_f32_e32 v8, v0, v8
	v_mul_f32_e32 v9, v0, v9
	v_mul_f32_e32 v10, v0, v10
	v_mul_f32_e32 v11, v0, v11
	ds_write_b32 v199, v4 offset:0
	ds_write_b32 v199, v5 offset:4
	ds_write_b32 v199, v6 offset:8
	ds_write_b32 v199, v7 offset:12
	ds_write_b32 v199, v8 offset:32
	ds_write_b32 v199, v9 offset:36
	ds_write_b32 v199, v10 offset:40
	ds_write_b32 v199, v11 offset:44
	ds_read_b32 v4, v20 offset:10240
	ds_read_b32 v5, v20 offset:10496
	ds_read_b32 v6, v20 offset:10752
	ds_read_b32 v7, v20 offset:11008
	ds_read_b32 v8, v20 offset:11264
	ds_read_b32 v9, v20 offset:11520
	ds_read_b32 v10, v20 offset:11776
	ds_read_b32 v11, v20 offset:12032
	ds_read_b32 v12, v20 offset:18432
	ds_read_b32 v13, v20 offset:18688
	ds_read_b32 v14, v20 offset:18944
	ds_read_b32 v15, v20 offset:19200
	ds_read_b32 v16, v20 offset:19456
	ds_read_b32 v17, v20 offset:19712
	ds_read_b32 v18, v20 offset:19968
	ds_read_b32 v19, v20 offset:20224
	s_waitcnt lgkmcnt(0)
; __device__ __forceinline__ int crow(int r, int hi) { return (r & 3) + 8 * (r >> 2) + 4 * hi; }
; __device__ __forceinline__ void sample_task(const Prm& P, Ctx& C, int task) {
;     ...
;         if (C.wave == 0) {
;             if (slot == ts) { const float gate = ((const float*)(P.ws + WS_G))[row * 24 + head * 3 + 0];
; #pragma unroll
;                 for (int dblk = 0; dblk < 2; ++dblk)
; #pragma unroll
;                     for (int r = 0; r < 16; ++r) ocs[g * 64 + 32 * dblk + crow(r, hi)] = oacc[(dblk * 16 + r) * 64 + lane] * gate; }
	v_add_f32_e32 v4, v4, v12
	v_add_f32_e32 v5, v5, v13
	v_add_f32_e32 v6, v6, v14
	v_add_f32_e32 v7, v7, v15
	v_add_f32_e32 v8, v8, v16
	v_add_f32_e32 v9, v9, v17
	v_add_f32_e32 v10, v10, v18
	v_add_f32_e32 v11, v11, v19
	ds_read_b32 v12, v20 offset:26624
	ds_read_b32 v13, v20 offset:26880
	ds_read_b32 v14, v20 offset:27136
	ds_read_b32 v15, v20 offset:27392
	ds_read_b32 v16, v20 offset:27648
	ds_read_b32 v17, v20 offset:27904
	ds_read_b32 v18, v20 offset:28160
	ds_read_b32 v19, v20 offset:28416
	s_waitcnt lgkmcnt(0)
	v_add_f32_e32 v4, v4, v12
	v_add_f32_e32 v5, v5, v13
	v_add_f32_e32 v6, v6, v14
	v_add_f32_e32 v7, v7, v15
	v_add_f32_e32 v8, v8, v16
	v_add_f32_e32 v9, v9, v17
	v_add_f32_e32 v10, v10, v18
	v_add_f32_e32 v11, v11, v19
	ds_read_b32 v12, v20 offset:34816
	ds_read_b32 v13, v20 offset:35072
	ds_read_b32 v14, v20 offset:35328
	ds_read_b32 v15, v20 offset:35584
	ds_read_b32 v16, v20 offset:35840
	ds_read_b32 v17, v20 offset:36096
	ds_read_b32 v18, v20 offset:36352
	ds_read_b32 v19, v20 offset:36608
	s_waitcnt lgkmcnt(0)
	v_add_f32_e32 v4, v4, v12
	v_add_f32_e32 v5, v5, v13
	v_add_f32_e32 v6, v6, v14
	v_add_f32_e32 v7, v7, v15
	v_add_f32_e32 v8, v8, v16
	v_add_f32_e32 v9, v9, v17
	v_add_f32_e32 v10, v10, v18
	v_add_f32_e32 v11, v11, v19
	ds_read_b32 v12, v21 offset:10240
	ds_read_b32 v13, v21 offset:10496
	ds_read_b32 v14, v21 offset:10752
	ds_read_b32 v15, v21 offset:11008
	ds_read_b32 v16, v21 offset:11264
	ds_read_b32 v17, v21 offset:11520
	ds_read_b32 v18, v21 offset:11776
	ds_read_b32 v19, v21 offset:12032
	s_waitcnt lgkmcnt(0)
	v_add_f32_e32 v4, v4, v12
	v_add_f32_e32 v5, v5, v13
	v_add_f32_e32 v6, v6, v14
	v_add_f32_e32 v7, v7, v15
	v_add_f32_e32 v8, v8, v16
	v_add_f32_e32 v9, v9, v17
	v_add_f32_e32 v10, v10, v18
	v_add_f32_e32 v11, v11, v19
	ds_read_b32 v12, v21 offset:18432
	ds_read_b32 v13, v21 offset:18688
	ds_read_b32 v14, v21 offset:18944
	ds_read_b32 v15, v21 offset:19200
	ds_read_b32 v16, v21 offset:19456
	ds_read_b32 v17, v21 offset:19712
	ds_read_b32 v18, v21 offset:19968
	ds_read_b32 v19, v21 offset:20224
	s_waitcnt lgkmcnt(0)
	v_add_f32_e32 v4, v4, v12
	v_add_f32_e32 v5, v5, v13
	v_add_f32_e32 v6, v6, v14
	v_add_f32_e32 v7, v7, v15
	v_add_f32_e32 v8, v8, v16
	v_add_f32_e32 v9, v9, v17
	v_add_f32_e32 v10, v10, v18
	v_add_f32_e32 v11, v11, v19
	ds_read_b32 v12, v21 offset:26624
	ds_read_b32 v13, v21 offset:26880
	ds_read_b32 v14, v21 offset:27136
	ds_read_b32 v15, v21 offset:27392
	ds_read_b32 v16, v21 offset:27648
	ds_read_b32 v17, v21 offset:27904
	ds_read_b32 v18, v21 offset:28160
	ds_read_b32 v19, v21 offset:28416
	s_waitcnt lgkmcnt(0)
	v_add_f32_e32 v4, v4, v12
	v_add_f32_e32 v5, v5, v13
	v_add_f32_e32 v6, v6, v14
	v_add_f32_e32 v7, v7, v15
	v_add_f32_e32 v8, v8, v16
	v_add_f32_e32 v9, v9, v17
	v_add_f32_e32 v10, v10, v18
	v_add_f32_e32 v11, v11, v19
	ds_read_b32 v12, v21 offset:34816
	ds_read_b32 v13, v21 offset:35072
	ds_read_b32 v14, v21 offset:35328
	ds_read_b32 v15, v21 offset:35584
	ds_read_b32 v16, v21 offset:35840
	ds_read_b32 v17, v21 offset:36096
	ds_read_b32 v18, v21 offset:36352
	ds_read_b32 v19, v21 offset:36608
	s_waitcnt lgkmcnt(0)
	v_add_f32_e32 v4, v4, v12
	v_add_f32_e32 v5, v5, v13
	v_add_f32_e32 v6, v6, v14
	v_add_f32_e32 v7, v7, v15
	v_add_f32_e32 v8, v8, v16
	v_add_f32_e32 v9, v9, v17
	v_add_f32_e32 v10, v10, v18
	v_add_f32_e32 v11, v11, v19
	v_mul_f32_e32 v4, v0, v4
	v_mul_f32_e32 v5, v0, v5
	v_mul_f32_e32 v6, v0, v6
	v_mul_f32_e32 v7, v0, v7
	v_mul_f32_e32 v8, v0, v8
	v_mul_f32_e32 v9, v0, v9
	v_mul_f32_e32 v10, v0, v10
	v_mul_f32_e32 v11, v0, v11
	ds_write_b32 v199, v4 offset:64
	ds_write_b32 v199, v5 offset:68
	ds_write_b32 v199, v6 offset:72
	ds_write_b32 v199, v7 offset:76
	ds_write_b32 v199, v8 offset:96
	ds_write_b32 v199, v9 offset:100
	ds_write_b32 v199, v10 offset:104
	ds_write_b32 v199, v11 offset:108
	ds_read_b32 v4, v20 offset:12288
	ds_read_b32 v5, v20 offset:12544
	ds_read_b32 v6, v20 offset:12800
	ds_read_b32 v7, v20 offset:13056
	ds_read_b32 v8, v20 offset:13312
	ds_read_b32 v9, v20 offset:13568
	ds_read_b32 v10, v20 offset:13824
	ds_read_b32 v11, v20 offset:14080
	ds_read_b32 v12, v20 offset:20480
	ds_read_b32 v13, v20 offset:20736
	ds_read_b32 v14, v20 offset:20992
	ds_read_b32 v15, v20 offset:21248
	ds_read_b32 v16, v20 offset:21504
	ds_read_b32 v17, v20 offset:21760
	ds_read_b32 v18, v20 offset:22016
	ds_read_b32 v19, v20 offset:22272
	s_waitcnt lgkmcnt(0)
	v_add_f32_e32 v4, v4, v12
	v_add_f32_e32 v5, v5, v13
	v_add_f32_e32 v6, v6, v14
	v_add_f32_e32 v7, v7, v15
	v_add_f32_e32 v8, v8, v16
	v_add_f32_e32 v9, v9, v17
	v_add_f32_e32 v10, v10, v18
	v_add_f32_e32 v11, v11, v19
	ds_read_b32 v12, v20 offset:28672
	ds_read_b32 v13, v20 offset:28928
	ds_read_b32 v14, v20 offset:29184
	ds_read_b32 v15, v20 offset:29440
	ds_read_b32 v16, v20 offset:29696
	ds_read_b32 v17, v20 offset:29952
	ds_read_b32 v18, v20 offset:30208
	ds_read_b32 v19, v20 offset:30464
	s_waitcnt lgkmcnt(0)
	v_add_f32_e32 v4, v4, v12
	v_add_f32_e32 v5, v5, v13
	v_add_f32_e32 v6, v6, v14
	v_add_f32_e32 v7, v7, v15
	v_add_f32_e32 v8, v8, v16
	v_add_f32_e32 v9, v9, v17
	v_add_f32_e32 v10, v10, v18
	v_add_f32_e32 v11, v11, v19
	ds_read_b32 v12, v20 offset:36864
	ds_read_b32 v13, v20 offset:37120
	ds_read_b32 v14, v20 offset:37376
	ds_read_b32 v15, v20 offset:37632
	ds_read_b32 v16, v20 offset:37888
	ds_read_b32 v17, v20 offset:38144
	ds_read_b32 v18, v20 offset:38400
	ds_read_b32 v19, v20 offset:38656
	s_waitcnt lgkmcnt(0)
; __device__ __forceinline__ int crow(int r, int hi) { return (r & 3) + 8 * (r >> 2) + 4 * hi; }
; __device__ __forceinline__ void sample_task(const Prm& P, Ctx& C, int task) {
;     ...
;         if (C.wave == 0) {
;             if (slot == ts) { const float gate = ((const float*)(P.ws + WS_G))[row * 24 + head * 3 + 0];
; #pragma unroll
;                 for (int dblk = 0; dblk < 2; ++dblk)
; #pragma unroll
;                     for (int r = 0; r < 16; ++r) ocs[g * 64 + 32 * dblk + crow(r, hi)] = oacc[(dblk * 16 + r) * 64 + lane] * gate; }
	v_add_f32_e32 v4, v4, v12
	v_add_f32_e32 v5, v5, v13
	v_add_f32_e32 v6, v6, v14
	v_add_f32_e32 v7, v7, v15
	v_add_f32_e32 v8, v8, v16
	v_add_f32_e32 v9, v9, v17
	v_add_f32_e32 v10, v10, v18
	v_add_f32_e32 v11, v11, v19
	ds_read_b32 v12, v21 offset:12288
	ds_read_b32 v13, v21 offset:12544
	ds_read_b32 v14, v21 offset:12800
	ds_read_b32 v15, v21 offset:13056
	ds_read_b32 v16, v21 offset:13312
	ds_read_b32 v17, v21 offset:13568
	ds_read_b32 v18, v21 offset:13824
	ds_read_b32 v19, v21 offset:14080
	s_waitcnt lgkmcnt(0)
	v_add_f32_e32 v4, v4, v12
	v_add_f32_e32 v5, v5, v13
	v_add_f32_e32 v6, v6, v14
	v_add_f32_e32 v7, v7, v15
	v_add_f32_e32 v8, v8, v16
	v_add_f32_e32 v9, v9, v17
	v_add_f32_e32 v10, v10, v18
	v_add_f32_e32 v11, v11, v19
	ds_read_b32 v12, v21 offset:20480
	ds_read_b32 v13, v21 offset:20736
	ds_read_b32 v14, v21 offset:20992
	ds_read_b32 v15, v21 offset:21248
	ds_read_b32 v16, v21 offset:21504
	ds_read_b32 v17, v21 offset:21760
	ds_read_b32 v18, v21 offset:22016
	ds_read_b32 v19, v21 offset:22272
	s_waitcnt lgkmcnt(0)
	v_add_f32_e32 v4, v4, v12
	v_add_f32_e32 v5, v5, v13
	v_add_f32_e32 v6, v6, v14
	v_add_f32_e32 v7, v7, v15
	v_add_f32_e32 v8, v8, v16
	v_add_f32_e32 v9, v9, v17
	v_add_f32_e32 v10, v10, v18
	v_add_f32_e32 v11, v11, v19
	ds_read_b32 v12, v21 offset:28672
	ds_read_b32 v13, v21 offset:28928
	ds_read_b32 v14, v21 offset:29184
	ds_read_b32 v15, v21 offset:29440
	ds_read_b32 v16, v21 offset:29696
	ds_read_b32 v17, v21 offset:29952
	ds_read_b32 v18, v21 offset:30208
	ds_read_b32 v19, v21 offset:30464
	s_waitcnt lgkmcnt(0)
	v_add_f32_e32 v4, v4, v12
	v_add_f32_e32 v5, v5, v13
	v_add_f32_e32 v6, v6, v14
	v_add_f32_e32 v7, v7, v15
	v_add_f32_e32 v8, v8, v16
	v_add_f32_e32 v9, v9, v17
	v_add_f32_e32 v10, v10, v18
	v_add_f32_e32 v11, v11, v19
	ds_read_b32 v12, v21 offset:36864
	ds_read_b32 v13, v21 offset:37120
	ds_read_b32 v14, v21 offset:37376
	ds_read_b32 v15, v21 offset:37632
	ds_read_b32 v16, v21 offset:37888
	ds_read_b32 v17, v21 offset:38144
	ds_read_b32 v18, v21 offset:38400
	ds_read_b32 v19, v21 offset:38656
	s_waitcnt lgkmcnt(0)
	v_add_f32_e32 v4, v4, v12
	v_add_f32_e32 v5, v5, v13
	v_add_f32_e32 v6, v6, v14
	v_add_f32_e32 v7, v7, v15
	v_add_f32_e32 v8, v8, v16
	v_add_f32_e32 v9, v9, v17
	v_add_f32_e32 v10, v10, v18
	v_add_f32_e32 v11, v11, v19
	v_mul_f32_e32 v4, v0, v4
	v_mul_f32_e32 v5, v0, v5
	v_mul_f32_e32 v6, v0, v6
	v_mul_f32_e32 v7, v0, v7
	v_mul_f32_e32 v8, v0, v8
	v_mul_f32_e32 v9, v0, v9
	v_mul_f32_e32 v10, v0, v10
	v_mul_f32_e32 v11, v0, v11
	ds_write_b32 v199, v4 offset:128
	ds_write_b32 v199, v5 offset:132
	ds_write_b32 v199, v6 offset:136
	ds_write_b32 v199, v7 offset:140
	ds_write_b32 v199, v8 offset:160
	ds_write_b32 v199, v9 offset:164
	ds_write_b32 v199, v10 offset:168
	ds_write_b32 v199, v11 offset:172
	ds_read_b32 v4, v20 offset:14336
	ds_read_b32 v5, v20 offset:14592
	ds_read_b32 v6, v20 offset:14848
	ds_read_b32 v7, v20 offset:15104
	ds_read_b32 v8, v20 offset:15360
	ds_read_b32 v9, v20 offset:15616
	ds_read_b32 v10, v20 offset:15872
	ds_read_b32 v11, v20 offset:16128
	ds_read_b32 v12, v20 offset:22528
	ds_read_b32 v13, v20 offset:22784
	ds_read_b32 v14, v20 offset:23040
	ds_read_b32 v15, v20 offset:23296
	ds_read_b32 v16, v20 offset:23552
	ds_read_b32 v17, v20 offset:23808
	ds_read_b32 v18, v20 offset:24064
	ds_read_b32 v19, v20 offset:24320
	s_waitcnt lgkmcnt(0)
; __device__ __forceinline__ int crow(int r, int hi) { return (r & 3) + 8 * (r >> 2) + 4 * hi; }
; __device__ __forceinline__ void sample_task(const Prm& P, Ctx& C, int task) {
;     ...
;         if (C.wave == 0) {
;             if (slot == ts) { const float gate = ((const float*)(P.ws + WS_G))[row * 24 + head * 3 + 0];
; #pragma unroll
;                 for (int dblk = 0; dblk < 2; ++dblk)
; #pragma unroll
;                     for (int r = 0; r < 16; ++r) ocs[g * 64 + 32 * dblk + crow(r, hi)] = oacc[(dblk * 16 + r) * 64 + lane] * gate; }
	v_add_f32_e32 v4, v4, v12
	v_add_f32_e32 v5, v5, v13
	v_add_f32_e32 v6, v6, v14
	v_add_f32_e32 v7, v7, v15
	v_add_f32_e32 v8, v8, v16
	v_add_f32_e32 v9, v9, v17
	v_add_f32_e32 v10, v10, v18
	v_add_f32_e32 v11, v11, v19
	ds_read_b32 v12, v20 offset:30720
	ds_read_b32 v13, v20 offset:30976
	ds_read_b32 v14, v20 offset:31232
	ds_read_b32 v15, v20 offset:31488
	ds_read_b32 v16, v20 offset:31744
	ds_read_b32 v17, v20 offset:32000
	ds_read_b32 v18, v20 offset:32256
	ds_read_b32 v19, v20 offset:32512
	s_waitcnt lgkmcnt(0)
	v_add_f32_e32 v4, v4, v12
	v_add_f32_e32 v5, v5, v13
	v_add_f32_e32 v6, v6, v14
	v_add_f32_e32 v7, v7, v15
	v_add_f32_e32 v8, v8, v16
	v_add_f32_e32 v9, v9, v17
	v_add_f32_e32 v10, v10, v18
	v_add_f32_e32 v11, v11, v19
	ds_read_b32 v12, v20 offset:38912
	ds_read_b32 v13, v20 offset:39168
	ds_read_b32 v14, v20 offset:39424
	ds_read_b32 v15, v20 offset:39680
	ds_read_b32 v16, v20 offset:39936
	ds_read_b32 v17, v20 offset:40192
	ds_read_b32 v18, v20 offset:40448
	ds_read_b32 v19, v20 offset:40704
	s_waitcnt lgkmcnt(0)
	v_add_f32_e32 v4, v4, v12
	v_add_f32_e32 v5, v5, v13
	v_add_f32_e32 v6, v6, v14
	v_add_f32_e32 v7, v7, v15
	v_add_f32_e32 v8, v8, v16
	v_add_f32_e32 v9, v9, v17
	v_add_f32_e32 v10, v10, v18
	v_add_f32_e32 v11, v11, v19
	ds_read_b32 v12, v21 offset:14336
	ds_read_b32 v13, v21 offset:14592
	ds_read_b32 v14, v21 offset:14848
	ds_read_b32 v15, v21 offset:15104
	ds_read_b32 v16, v21 offset:15360
	ds_read_b32 v17, v21 offset:15616
	ds_read_b32 v18, v21 offset:15872
	ds_read_b32 v19, v21 offset:16128
	s_waitcnt lgkmcnt(0)
	v_add_f32_e32 v4, v4, v12
	v_add_f32_e32 v5, v5, v13
	v_add_f32_e32 v6, v6, v14
	v_add_f32_e32 v7, v7, v15
	v_add_f32_e32 v8, v8, v16
	v_add_f32_e32 v9, v9, v17
	v_add_f32_e32 v10, v10, v18
	v_add_f32_e32 v11, v11, v19
	ds_read_b32 v12, v21 offset:22528
	ds_read_b32 v13, v21 offset:22784
	ds_read_b32 v14, v21 offset:23040
	ds_read_b32 v15, v21 offset:23296
	ds_read_b32 v16, v21 offset:23552
	ds_read_b32 v17, v21 offset:23808
	ds_read_b32 v18, v21 offset:24064
	ds_read_b32 v19, v21 offset:24320
	s_waitcnt lgkmcnt(0)
	v_add_f32_e32 v4, v4, v12
	v_add_f32_e32 v5, v5, v13
	v_add_f32_e32 v6, v6, v14
	v_add_f32_e32 v7, v7, v15
	v_add_f32_e32 v8, v8, v16
	v_add_f32_e32 v9, v9, v17
	v_add_f32_e32 v10, v10, v18
	v_add_f32_e32 v11, v11, v19
	ds_read_b32 v12, v21 offset:30720
	ds_read_b32 v13, v21 offset:30976
	ds_read_b32 v14, v21 offset:31232
	ds_read_b32 v15, v21 offset:31488
	ds_read_b32 v16, v21 offset:31744
	ds_read_b32 v17, v21 offset:32000
	ds_read_b32 v18, v21 offset:32256
	ds_read_b32 v19, v21 offset:32512
	s_waitcnt lgkmcnt(0)
	v_add_f32_e32 v4, v4, v12
	v_add_f32_e32 v5, v5, v13
	v_add_f32_e32 v6, v6, v14
	v_add_f32_e32 v7, v7, v15
	v_add_f32_e32 v8, v8, v16
	v_add_f32_e32 v9, v9, v17
	v_add_f32_e32 v10, v10, v18
	v_add_f32_e32 v11, v11, v19
	ds_read_b32 v12, v21 offset:38912
	ds_read_b32 v13, v21 offset:39168
	ds_read_b32 v14, v21 offset:39424
	ds_read_b32 v15, v21 offset:39680
	ds_read_b32 v16, v21 offset:39936
	ds_read_b32 v17, v21 offset:40192
	ds_read_b32 v18, v21 offset:40448
	ds_read_b32 v19, v21 offset:40704
	s_waitcnt lgkmcnt(0)
	v_add_f32_e32 v4, v4, v12
	v_add_f32_e32 v5, v5, v13
	v_add_f32_e32 v6, v6, v14
	v_add_f32_e32 v7, v7, v15
	v_add_f32_e32 v8, v8, v16
	v_add_f32_e32 v9, v9, v17
	v_add_f32_e32 v10, v10, v18
	v_add_f32_e32 v11, v11, v19
	v_mul_f32_e32 v4, v0, v4
	v_mul_f32_e32 v5, v0, v5
	v_mul_f32_e32 v6, v0, v6
	v_mul_f32_e32 v7, v0, v7
	v_mul_f32_e32 v8, v0, v8
	v_mul_f32_e32 v9, v0, v9
	v_mul_f32_e32 v10, v0, v10
	v_mul_f32_e32 v11, v0, v11
	ds_write_b32 v199, v4 offset:192
	ds_write_b32 v199, v5 offset:196
	ds_write_b32 v199, v6 offset:200
	ds_write_b32 v199, v7 offset:204
	ds_write_b32 v199, v8 offset:224
	ds_write_b32 v199, v9 offset:228
	ds_write_b32 v199, v10 offset:232
	ds_write_b32 v199, v11 offset:236

; #define LAS __attribute__((address_space(3)))
; template <int NBL>
; __device__ __forceinline__ unsigned topk_select(const LAS float* sc  , int sub, int cur) {
;     unsigned v[NBL]; unsigned candm = 0u, forced = 0u;
; #pragma unroll
;     for (int e = 0; e < NBL; ++e) { const int j = sub * NBL + e; const bool cand = (j >= 1) && (j <= cur - 2);
;         v[e] = cand ? __float_as_uint(sc[j]) : 0u; if (cand) candm |= 1u << e;
;         if (j == 0 || j == cur || (j == cur - 1 && cur >= 1)) forced |= 1u << e; }
;     const int nf = cur == 0 ? 1 : (cur == 1 ? 2 : 3), kk = 16 - nf, ncand = cur - 2 > 0 ? cur - 2 : 0;
;     unsigned prefix = 0u;
;     {
;         unsigned ceil_ = 0xFFFFFFFFu; int taken = 0; bool done = ncand <= kk;
; __device__ __forceinline__ void sample_task(const Prm& P, Ctx& C, int task) {
;     ...
;             const int slot2 = lane >> 3, sub = lane & 7;
;             const unsigned bits = topk_select<32>(sc + slot2 * 256, sub, 256);
.Lw0_topk:
	v_mov_b32_e32 v32, 0x7ffffffe
	v_mov_b32_e32 v0, 0
	v_mov_b32_e32 v34, 0
	s_mov_b64 s[0:1], exec
	v_readlane_b32 s2, v253, 13
	v_readlane_b32 s3, v253, 14
	s_and_b64 s[2:3], s[0:1], s[2:3]
	s_mov_b64 exec, s[2:3]
	ds_read_b32 v34, v189
	v_bfrev_b32_e32 v32, -2
	s_or_b64 exec, exec, s[0:1]
	ds_read2_b32 v[30:31], v189 offset0:1 offset1:2
	ds_read2_b32 v[28:29], v189 offset0:3 offset1:4
	ds_read2_b32 v[26:27], v189 offset0:5 offset1:6
	ds_read2_b32 v[24:25], v189 offset0:7 offset1:8
	ds_read2_b32 v[22:23], v189 offset0:9 offset1:10
	ds_read2_b32 v[20:21], v189 offset0:11 offset1:12
	ds_read2_b32 v[18:19], v189 offset0:13 offset1:14
	ds_read2_b32 v[16:17], v189 offset0:15 offset1:16
	ds_read2_b32 v[14:15], v189 offset0:17 offset1:18
	ds_read2_b32 v[12:13], v189 offset0:19 offset1:20
	ds_read2_b32 v[10:11], v189 offset0:21 offset1:22
	ds_read2_b32 v[8:9], v189 offset0:23 offset1:24
	ds_read2_b32 v[6:7], v189 offset0:25 offset1:26
	ds_read2_b32 v[4:5], v189 offset0:27 offset1:28
	ds_read2_b32 v[2:3], v189 offset0:29 offset1:30
	s_mov_b64 s[0:1], exec
	v_readlane_b32 s2, v253, 21
	v_readlane_b32 s3, v253, 22
	s_and_b64 s[2:3], s[0:1], s[2:3]
	v_readlane_b32 s8, v251, 2
	s_mov_b64 exec, s[2:3]
	ds_read_b32 v0, v189 offset:124
	v_or_b32_e32 v32, 0x80000000, v32
	s_or_b64 exec, exec, s[0:1]
	s_mov_b64 s[2:3], 0
	v_mov_b32_e32 v35, -1
	v_mov_b32_e32 v33, 0
	v_mov_b32_e32 v36, 14
	v_mov_b32_e32 v37, 0
	s_branch .LBB0_1535
